# GDN scan: compute waves at s_setprio 3 over the chunk loop (static wave priority, strategy 4)
# baseline (speedup 1.0000x reference)
; #define GAS __attribute__((address_space(1)))
;     ...
;     if (wave < 4) {
;         f32x4 S[2][8];
; #pragma unroll
;         for (int n = 0; n < 2; ++n)
; #pragma unroll
;             for (int i = 0; i < 8; ++i) S[n][i] = (f32x4){0.f, 0.f, 0.f, 0.f};
;         float ebs = ge[lane];
;         asm volatile("" : "+v"(ebs));
;         v2u ua[2][4], ub[2][4];
; #pragma unroll
;         for (int n = 0; n < 2; ++n)
; #pragma unroll
;             for (int mt = 0; mt < 4; ++mt) ua[n][mt] = *(const GAS v2u*)(gu + (size_t)(((2 * wave + n) * 4 + mt) * 64 + lane) * 8);
; #pragma unroll 1
.LBB0_986:
	s_andn2_b64 vcc, exec, s[30:31]
	s_cbranch_vccnz .LBB0_990
	v_readlane_b32 s30, v254, 44
	v_readlane_b32 s31, v254, 45
	s_add_u32 s30, s0, s30
	s_addc_u32 s31, s1, s31
	s_add_u32 s40, s30, 0x42850000
	s_addc_u32 s41, s31, 0
	v_readlane_b32 s38, v253, 46
	v_readlane_b32 s39, v253, 47
	s_add_u32 s0, s0, s38
	s_addc_u32 s1, s1, s39
	v_lshlrev_b32_e32 v96, 2, v146
	s_waitcnt vmcnt(0)
	v_lshl_add_u64 v[0:1], s[0:1], 0, v[96:97]
	s_mov_b32 s0, 0x44050000
	v_add_co_u32_e32 v0, vcc, s0, v0
	v_and_b32_e32 v16, 15, v101
	s_nop 0
	v_addc_co_u32_e32 v1, vcc, 0, v1, vcc
	flat_load_dword v96, v[0:1]
	v_lshl_or_b32 v0, s36, 9, v146
	v_ashrrev_i32_e32 v1, 31, v0
	v_or_b32_e32 v2, 64, v0
	v_or_b32_e32 v4, 0x80, v0
	v_or_b32_e32 v6, 0xc0, v0
	v_or_b32_e32 v8, 0x100, v0
	v_or_b32_e32 v10, 0x140, v0
	v_or_b32_e32 v12, 0x180, v0
	v_or_b32_e32 v14, 0x1c0, v0
	v_lshlrev_b64 v[98:99], 3, v[0:1]
	v_ashrrev_i32_e32 v3, 31, v2
	v_ashrrev_i32_e32 v5, 31, v4
	v_ashrrev_i32_e32 v7, 31, v6
	v_ashrrev_i32_e32 v9, 31, v8
	v_ashrrev_i32_e32 v11, 31, v10
	v_ashrrev_i32_e32 v13, 31, v12
	v_ashrrev_i32_e32 v15, 31, v14
	v_lshl_add_u32 v101, v146, 4, 0
	v_lshrrev_b32_e32 v17, 2, v146
	v_lshlrev_b64 v[134:135], 3, v[2:3]
	v_lshlrev_b64 v[136:137], 3, v[4:5]
	v_lshlrev_b64 v[138:139], 3, v[6:7]
	v_lshlrev_b64 v[140:141], 3, v[8:9]
	v_lshlrev_b64 v[142:143], 3, v[10:11]
	v_lshlrev_b64 v[144:145], 3, v[12:13]
	v_lshlrev_b64 v[146:147], 3, v[14:15]
	v_lshl_add_u64 v[0:1], s[40:41], 0, v[98:99]
	v_lshl_add_u64 v[2:3], s[40:41], 0, v[134:135]
	v_lshl_add_u64 v[4:5], s[40:41], 0, v[136:137]
	v_lshl_add_u64 v[6:7], s[40:41], 0, v[138:139]
	v_lshl_add_u64 v[8:9], s[40:41], 0, v[140:141]
	v_lshl_add_u64 v[10:11], s[40:41], 0, v[142:143]
	v_lshl_add_u64 v[12:13], s[40:41], 0, v[144:145]
	v_lshl_add_u64 v[14:15], s[40:41], 0, v[146:147]
	s_waitcnt vmcnt(0) lgkmcnt(0)
	global_load_dwordx2 v[178:179], v[0:1], off
	global_load_dwordx2 v[174:175], v[2:3], off
	global_load_dwordx2 v[170:171], v[4:5], off
	global_load_dwordx2 v[164:165], v[6:7], off
	global_load_dwordx2 v[176:177], v[8:9], off
	global_load_dwordx2 v[172:173], v[10:11], off
	global_load_dwordx2 v[168:169], v[12:13], off
	global_load_dwordx2 v[166:167], v[14:15], off
	s_lshl_b32 s0, s36, 7
	s_add_i32 s0, s0, 0
	v_and_b32_e32 v18, 12, v17
	s_add_i32 s0, s0, 0x1c000
	v_or_b32_e32 v0, 3, v17
	v_lshl_add_u32 v1, v16, 2, s0
	v_mul_u32_u24_e32 v2, 0x210, v18
	v_mul_u32_u24_e32 v3, 0x210, v0
	s_mov_b64 s[38:39], 0x42854000
	v_mov_b32_e32 v0, 0
	s_mov_b32 s1, 0
	v_add_u32_e32 v200, 0xe000, v101
	v_lshl_add_u64 v[148:149], v[146:147], 0, s[38:39]
	v_lshl_add_u64 v[150:151], v[144:145], 0, s[38:39]
	v_lshl_add_u64 v[152:153], v[142:143], 0, s[38:39]
	v_lshl_add_u64 v[154:155], v[140:141], 0, s[38:39]
	v_lshl_add_u64 v[156:157], v[138:139], 0, s[38:39]
	v_lshl_add_u64 v[158:159], v[136:137], 0, s[38:39]
	v_lshl_add_u64 v[160:161], v[134:135], 0, s[38:39]
	v_lshl_add_u64 v[162:163], v[98:99], 0, s[38:39]
	v_add_u32_e32 v201, v1, v2
	v_add_u32_e32 v202, v1, v3
	v_mov_b32_e32 v1, v0
	v_mov_b32_e32 v2, v0
	v_mov_b32_e32 v3, v0
	v_mov_b32_e32 v4, v0
	v_mov_b32_e32 v5, v0
	v_mov_b32_e32 v6, v0
	v_mov_b32_e32 v7, v0
	v_mov_b32_e32 v8, v0
	v_mov_b32_e32 v9, v0
	v_mov_b32_e32 v10, v0
	v_mov_b32_e32 v11, v0
	v_mov_b32_e32 v12, v0
	v_mov_b32_e32 v13, v0
	v_mov_b32_e32 v14, v0
	v_mov_b32_e32 v15, v0
	v_mov_b32_e32 v16, v0
	v_mov_b32_e32 v17, v0
	v_mov_b32_e32 v18, v0
	v_mov_b32_e32 v19, v0
	v_mov_b32_e32 v24, v0
	v_mov_b32_e32 v25, v0
	v_mov_b32_e32 v26, v0
	v_mov_b32_e32 v27, v0
	v_mov_b32_e32 v32, v0
	v_mov_b32_e32 v33, v0
	v_mov_b32_e32 v34, v0
	v_mov_b32_e32 v35, v0
	v_mov_b32_e32 v40, v0
	v_mov_b32_e32 v41, v0
	v_mov_b32_e32 v42, v0
	v_mov_b32_e32 v43, v0
	v_mov_b32_e32 v20, v0
	v_mov_b32_e32 v21, v0
	v_mov_b32_e32 v22, v0
	v_mov_b32_e32 v23, v0
	v_mov_b32_e32 v28, v0
	v_mov_b32_e32 v29, v0
	v_mov_b32_e32 v30, v0
	v_mov_b32_e32 v31, v0
	v_mov_b32_e32 v36, v0
	v_mov_b32_e32 v37, v0
	v_mov_b32_e32 v38, v0
	v_mov_b32_e32 v39, v0
	v_mov_b32_e32 v44, v0
	v_mov_b32_e32 v45, v0
	v_mov_b32_e32 v46, v0
	v_mov_b32_e32 v47, v0
	v_mov_b32_e32 v48, v0
	v_mov_b32_e32 v49, v0
	v_mov_b32_e32 v50, v0
	v_mov_b32_e32 v51, v0
	v_mov_b32_e32 v52, v0
	v_mov_b32_e32 v53, v0
	v_mov_b32_e32 v54, v0
	v_mov_b32_e32 v55, v0
	v_mov_b32_e32 v56, v0
	v_mov_b32_e32 v57, v0
	v_mov_b32_e32 v58, v0
	v_mov_b32_e32 v59, v0
	v_mov_b32_e32 v60, v0
	v_mov_b32_e32 v61, v0
	v_mov_b32_e32 v62, v0
	v_mov_b32_e32 v63, v0
	s_setprio 3
;     ...
; #pragma unroll
;             for (int n = 0; n < 2; ++n)
; #pragma unroll
;                 for (int mt = 0; mt < 4; ++mt) ub[n][mt] = *(const GAS v2u*)(gu + (size_t)cn * 16384 + (size_t)(((2 * wave + n) * 4 + mt) * 64 + lane) * 8);
;             const float eb = __builtin_bit_cast(float, __builtin_amdgcn_readlane(__builtin_bit_cast(int, ebs), ch));
;             __builtin_amdgcn_sched_barrier(0);
;             bf16x8 Sb[2][4];
; #pragma unroll
;             for (int n = 0; n < 2; ++n)
; #pragma unroll
;                 for (int kb = 0; kb < 4; ++kb) Sb[n][kb] = pack_b(S[n][2 * kb], S[n][2 * kb + 1]);
;             const LAS unsigned char* B0l = B0 + lane * 16;
;             bf16x8 fr0[4], fr1[4];
;             f32x4 o[2][4], vn[2][4]; bf16x8 Vb[2][2];
; #pragma unroll
;             for (int n = 0; n < 2; ++n)
; #pragma unroll
;                 for (int mt = 0; mt < 4; ++mt) o[n][mt] = (f32x4){0.f, 0.f, 0.f, 0.f};
;             if (!(variant & 2)) {
;             fr0[0] = *(const LAS bf16x8*)(B0l + 16384 + 0*1024 + 0*1024); fr0[1] = *(const LAS bf16x8*)(B0l + 16384 + 0*1024 + 1*1024); fr0[2] = *(const LAS bf16x8*)(B0l + 16384 + 0*1024 + 2*1024); fr0[3] = *(const LAS bf16x8*)(B0l + 16384 + 0*1024 + 3*1024);
;             fr1[0] = *(const LAS bf16x8*)(B0l + 16384 + 4*1024 + 0*1024); fr1[1] = *(const LAS bf16x8*)(B0l + 16384 + 4*1024 + 1*1024); fr1[2] = *(const LAS bf16x8*)(B0l + 16384 + 4*1024 + 2*1024); fr1[3] = *(const LAS bf16x8*)(B0l + 16384 + 4*1024 + 3*1024);
;             __builtin_amdgcn_sched_barrier(0);
;             { f32x4 c0 = {0.f, 0.f, 0.f, 0.f}, c1 = {0.f, 0.f, 0.f, 0.f};
;               c0 = MFMA16(fr0[0], Sb[0][0], c0); c1 = MFMA16(fr0[0], Sb[1][0], c1);
;               c0 = MFMA16(fr0[1], Sb[0][1], c0); c1 = MFMA16(fr0[1], Sb[1][1], c1);
;               c0 = MFMA16(fr0[2], Sb[0][2], c0); c1 = MFMA16(fr0[2], Sb[1][2], c1);
;               c0 = MFMA16(fr0[3], Sb[0][3], c0); c1 = MFMA16(fr0[3], Sb[1][3], c1);
;               o[0][0] = c0; o[1][0] = c1; }
;             __builtin_amdgcn_sched_barrier(0);
;             fr0[0] = *(const LAS bf16x8*)(B0l + 16384 + 8*1024 + 0*1024); fr0[1] = *(const LAS bf16x8*)(B0l + 16384 + 8*1024 + 1*1024); fr0[2] = *(const LAS bf16x8*)(B0l + 16384 + 8*1024 + 2*1024); fr0[3] = *(const LAS bf16x8*)(B0l + 16384 + 8*1024 + 3*1024);
;             __builtin_amdgcn_sched_barrier(0);
.LBB0_988:
	v_lshl_add_u64 v[64:65], s[30:31], 0, v[162:163]
	v_lshl_add_u64 v[66:67], s[30:31], 0, v[160:161]
	v_lshl_add_u64 v[68:69], s[30:31], 0, v[158:159]
	v_lshl_add_u64 v[70:71], s[30:31], 0, v[156:157]
	global_load_dwordx2 v[198:199], v[64:65], off
	global_load_dwordx2 v[194:195], v[66:67], off
	global_load_dwordx2 v[190:191], v[68:69], off
	global_load_dwordx2 v[180:181], v[70:71], off
	v_lshl_add_u64 v[64:65], s[30:31], 0, v[154:155]
	v_lshl_add_u64 v[66:67], s[30:31], 0, v[152:153]
	v_lshl_add_u64 v[68:69], s[30:31], 0, v[150:151]
	v_lshl_add_u64 v[70:71], s[30:31], 0, v[148:149]
	global_load_dwordx2 v[196:197], v[64:65], off
	global_load_dwordx2 v[192:193], v[66:67], off
	global_load_dwordx2 v[188:189], v[68:69], off
	global_load_dwordx2 v[186:187], v[70:71], off
	s_add_i32 s2, s1, 1
	ds_read_b128 v[92:95], v101 offset:16384
	ds_read_b128 v[102:105], v101 offset:17408
	ds_read_b128 v[106:109], v101 offset:18432
	ds_read_b128 v[110:113], v101 offset:19456
	ds_read_b128 v[118:121], v101 offset:20480
	ds_read_b128 v[122:125], v101 offset:21504
	ds_read_b128 v[126:129], v101 offset:22528
	ds_read_b128 v[130:133], v101 offset:23552
	v_cvt_pk_bf16_f32 v64, v0, v1
	v_cvt_pk_bf16_f32 v65, v2, v3
	v_cvt_pk_bf16_f32 v66, v4, v5
	v_cvt_pk_bf16_f32 v67, v6, v7
	v_cvt_pk_bf16_f32 v68, v8, v9
	v_cvt_pk_bf16_f32 v69, v10, v11
	v_cvt_pk_bf16_f32 v70, v12, v13
	v_cvt_pk_bf16_f32 v71, v14, v15
	v_cvt_pk_bf16_f32 v72, v16, v17
	v_cvt_pk_bf16_f32 v73, v18, v19
	v_cvt_pk_bf16_f32 v74, v24, v25
	v_cvt_pk_bf16_f32 v75, v26, v27
	v_cvt_pk_bf16_f32 v76, v32, v33
	v_cvt_pk_bf16_f32 v77, v34, v35
	v_cvt_pk_bf16_f32 v78, v40, v41
	v_cvt_pk_bf16_f32 v79, v42, v43
	v_cvt_pk_bf16_f32 v80, v20, v21
	v_cvt_pk_bf16_f32 v81, v22, v23
	v_cvt_pk_bf16_f32 v82, v28, v29
	v_cvt_pk_bf16_f32 v83, v30, v31
	v_cvt_pk_bf16_f32 v84, v36, v37
	v_cvt_pk_bf16_f32 v85, v38, v39
	v_cvt_pk_bf16_f32 v86, v44, v45
	v_cvt_pk_bf16_f32 v87, v46, v47
	v_cvt_pk_bf16_f32 v88, v48, v49
	v_cvt_pk_bf16_f32 v89, v50, v51
	v_cvt_pk_bf16_f32 v90, v52, v53
	v_cvt_pk_bf16_f32 v91, v54, v55
	v_cvt_pk_bf16_f32 v114, v56, v57
	v_cvt_pk_bf16_f32 v115, v58, v59
	v_cvt_pk_bf16_f32 v116, v60, v61
	v_cvt_pk_bf16_f32 v117, v62, v63
	v_readlane_b32 s0, v96, s1
	s_waitcnt lgkmcnt(7)
	v_mfma_f32_16x16x32_bf16 v[204:207], v[92:95], v[64:67], 0
	v_mfma_f32_16x16x32_bf16 v[92:95], v[92:95], v[80:83], 0
	s_waitcnt lgkmcnt(6)
	v_mfma_f32_16x16x32_bf16 v[204:207], v[102:105], v[68:71], v[204:207]
	v_mfma_f32_16x16x32_bf16 v[92:95], v[102:105], v[84:87], v[92:95]
	s_waitcnt lgkmcnt(5)
	v_mfma_f32_16x16x32_bf16 v[102:105], v[106:109], v[72:75], v[204:207]
	v_mfma_f32_16x16x32_bf16 v[106:109], v[106:109], v[88:91], v[92:95]
	s_waitcnt lgkmcnt(4)
	v_mfma_f32_16x16x32_bf16 v[92:95], v[110:113], v[76:79], v[102:105]
	v_mfma_f32_16x16x32_bf16 v[102:105], v[110:113], v[114:117], v[106:109]
	v_pk_mul_f32 v[2:3], v[2:3], s[0:1] op_sel_hi:[1,0]
	v_pk_mul_f32 v[0:1], v[0:1], s[0:1] op_sel_hi:[1,0]
	v_pk_mul_f32 v[22:23], v[22:23], s[0:1] op_sel_hi:[1,0]
	v_pk_mul_f32 v[20:21], v[20:21], s[0:1] op_sel_hi:[1,0]
	v_pk_mul_f32 v[6:7], v[6:7], s[0:1] op_sel_hi:[1,0]
	s_nop 0
	ds_read_b128 v[204:207], v101 offset:24576
	ds_read_b128 v[208:211], v101 offset:25600
	ds_read_b128 v[212:215], v101 offset:26624
	ds_read_b128 v[216:219], v101 offset:27648
	s_waitcnt lgkmcnt(7)
	v_mfma_f32_16x16x32_bf16 v[106:109], v[118:121], v[64:67], 0
	v_mfma_f32_16x16x32_bf16 v[110:113], v[118:121], v[80:83], 0
	s_waitcnt lgkmcnt(6)
	v_mfma_f32_16x16x32_bf16 v[106:109], v[122:125], v[68:71], v[106:109]
	v_mfma_f32_16x16x32_bf16 v[110:113], v[122:125], v[84:87], v[110:113]
	s_waitcnt lgkmcnt(5)
	v_mfma_f32_16x16x32_bf16 v[106:109], v[126:129], v[72:75], v[106:109]
	v_mfma_f32_16x16x32_bf16 v[110:113], v[126:129], v[88:91], v[110:113]
	s_waitcnt lgkmcnt(4)
	v_mfma_f32_16x16x32_bf16 v[106:109], v[130:133], v[76:79], v[106:109]
	v_mfma_f32_16x16x32_bf16 v[110:113], v[130:133], v[114:117], v[110:113]
	v_pk_mul_f32 v[4:5], v[4:5], s[0:1] op_sel_hi:[1,0]
	v_pk_mul_f32 v[30:31], v[30:31], s[0:1] op_sel_hi:[1,0]
	v_pk_mul_f32 v[28:29], v[28:29], s[0:1] op_sel_hi:[1,0]
	v_pk_mul_f32 v[10:11], v[10:11], s[0:1] op_sel_hi:[1,0]
	ds_read_b128 v[126:129], v101 offset:28672
	ds_read_b128 v[130:133], v101 offset:29696
	ds_read_b128 v[220:223], v101 offset:30720
	ds_read_b128 v[234:237], v101 offset:31744
	s_waitcnt lgkmcnt(7)
	v_mfma_f32_16x16x32_bf16 v[118:121], v[204:207], v[64:67], 0
	v_mfma_f32_16x16x32_bf16 v[122:125], v[204:207], v[80:83], 0
	s_waitcnt lgkmcnt(6)
	v_mfma_f32_16x16x32_bf16 v[118:121], v[208:211], v[68:71], v[118:121]
	v_mfma_f32_16x16x32_bf16 v[122:125], v[208:211], v[84:87], v[122:125]
	s_waitcnt lgkmcnt(5)
	v_mfma_f32_16x16x32_bf16 v[118:121], v[212:215], v[72:75], v[118:121]
	v_mfma_f32_16x16x32_bf16 v[122:125], v[212:215], v[88:91], v[122:125]
	s_waitcnt lgkmcnt(4)
	v_mfma_f32_16x16x32_bf16 v[118:121], v[216:219], v[76:79], v[118:121]
	v_mfma_f32_16x16x32_bf16 v[122:125], v[216:219], v[114:117], v[122:125]
	v_pk_mul_f32 v[8:9], v[8:9], s[0:1] op_sel_hi:[1,0]
	v_pk_mul_f32 v[38:39], v[38:39], s[0:1] op_sel_hi:[1,0]
	v_pk_mul_f32 v[36:37], v[36:37], s[0:1] op_sel_hi:[1,0]
	v_pk_mul_f32 v[14:15], v[14:15], s[0:1] op_sel_hi:[1,0]
	ds_read_b128 v[204:207], v101
	ds_read_b128 v[208:211], v101 offset:1024
	ds_read_b128 v[212:215], v101 offset:2048
	ds_read_b128 v[216:219], v101 offset:3072
	s_waitcnt lgkmcnt(7)
	v_mfma_f32_16x16x32_bf16 v[238:241], v[126:129], v[64:67], 0
	v_mfma_f32_16x16x32_bf16 v[126:129], v[126:129], v[80:83], 0
	s_waitcnt lgkmcnt(6)
	v_mfma_f32_16x16x32_bf16 v[238:241], v[130:133], v[68:71], v[238:241]
	v_mfma_f32_16x16x32_bf16 v[126:129], v[130:133], v[84:87], v[126:129]
	s_waitcnt lgkmcnt(5)
;     ...
;             fr0[0] = *(const LAS bf16x8*)(B0l + 0*1024 + 0*1024); fr0[1] = *(const LAS bf16x8*)(B0l + 0*1024 + 1*1024); fr0[2] = *(const LAS bf16x8*)(B0l + 0*1024 + 2*1024); fr0[3] = *(const LAS bf16x8*)(B0l + 0*1024 + 3*1024);
;             __builtin_amdgcn_sched_barrier(0);
;             { f32x4 c0 = {0.f, 0.f, 0.f, 0.f}, c1 = {0.f, 0.f, 0.f, 0.f};
;               c0 = MFMA16(fr1[0], Sb[0][0], c0); c1 = MFMA16(fr1[0], Sb[1][0], c1);
;               c0 = MFMA16(fr1[1], Sb[0][1], c0); c1 = MFMA16(fr1[1], Sb[1][1], c1);
;               c0 = MFMA16(fr1[2], Sb[0][2], c0); c1 = MFMA16(fr1[2], Sb[1][2], c1);
;               c0 = MFMA16(fr1[3], Sb[0][3], c0); c1 = MFMA16(fr1[3], Sb[1][3], c1);
;               o[0][3] = c0; o[1][3] = c1; }
;             __builtin_amdgcn_sched_barrier(0);
;             fr1[0] = *(const LAS bf16x8*)(B0l + 4*1024 + 0*1024); fr1[1] = *(const LAS bf16x8*)(B0l + 4*1024 + 1*1024); fr1[2] = *(const LAS bf16x8*)(B0l + 4*1024 + 2*1024); fr1[3] = *(const LAS bf16x8*)(B0l + 4*1024 + 3*1024);
;             __builtin_amdgcn_sched_barrier(0);
;             { f32x4 a0 = {0.f, 0.f, 0.f, 0.f}, a1 = {0.f, 0.f, 0.f, 0.f};
;               a0 = MFMA16(fr0[0], Sb[0][0], a0); a1 = MFMA16(fr0[0], Sb[1][0], a1);
;               a0 = MFMA16(fr0[1], Sb[0][1], a0); a1 = MFMA16(fr0[1], Sb[1][1], a1);
;               a0 = MFMA16(fr0[2], Sb[0][2], a0); a1 = MFMA16(fr0[2], Sb[1][2], a1);
;               a0 = MFMA16(fr0[3], Sb[0][3], a0); a1 = MFMA16(fr0[3], Sb[1][3], a1);
;               vn[0][0] = (f32x4){bflo(ua[0][0].x), bfhi(ua[0][0].x), bflo(ua[0][0].y), bfhi(ua[0][0].y)} - a0; vn[1][0] = (f32x4){bflo(ua[1][0].x), bfhi(ua[1][0].x), bflo(ua[1][0].y), bfhi(ua[1][0].y)} - a1; }
;             __builtin_amdgcn_sched_barrier(0);
;             fr0[0] = *(const LAS bf16x8*)(B0l + 8*1024 + 0*1024); fr0[1] = *(const LAS bf16x8*)(B0l + 8*1024 + 1*1024); fr0[2] = *(const LAS bf16x8*)(B0l + 8*1024 + 2*1024); fr0[3] = *(const LAS bf16x8*)(B0l + 8*1024 + 3*1024);
;             __builtin_amdgcn_sched_barrier(0);
;             { f32x4 a0 = {0.f, 0.f, 0.f, 0.f}, a1 = {0.f, 0.f, 0.f, 0.f};
;               a0 = MFMA16(fr1[0], Sb[0][0], a0); a1 = MFMA16(fr1[0], Sb[1][0], a1);
;               a0 = MFMA16(fr1[1], Sb[0][1], a0); a1 = MFMA16(fr1[1], Sb[1][1], a1);
;               a0 = MFMA16(fr1[2], Sb[0][2], a0); a1 = MFMA16(fr1[2], Sb[1][2], a1);
	v_mfma_f32_16x16x32_bf16 v[130:133], v[220:223], v[72:75], v[238:241]
	v_mfma_f32_16x16x32_bf16 v[220:223], v[220:223], v[88:91], v[126:129]
	s_waitcnt lgkmcnt(4)
	v_mfma_f32_16x16x32_bf16 v[126:129], v[234:237], v[76:79], v[130:133]
	v_mfma_f32_16x16x32_bf16 v[130:133], v[234:237], v[114:117], v[220:223]
	v_pk_mul_f32 v[12:13], v[12:13], s[0:1] op_sel_hi:[1,0]
	v_pk_mul_f32 v[46:47], v[46:47], s[0:1] op_sel_hi:[1,0]
	v_pk_mul_f32 v[44:45], v[44:45], s[0:1] op_sel_hi:[1,0]
	v_pk_mul_f32 v[18:19], v[18:19], s[0:1] op_sel_hi:[1,0]
	s_nop 4
	ds_read_b128 v[220:223], v101 offset:4096
	ds_read_b128 v[234:237], v101 offset:5120
	ds_read_b128 v[238:241], v101 offset:6144
	ds_read_b128 v[242:245], v101 offset:7168
	s_waitcnt lgkmcnt(7)
	v_mfma_f32_16x16x32_bf16 v[246:249], v[204:207], v[64:67], 0
	s_waitcnt vmcnt(15)
	v_lshlrev_b32_e32 v203, 16, v178
	v_and_b32_e32 v178, 0xffff0000, v178
	v_mfma_f32_16x16x32_bf16 v[204:207], v[204:207], v[80:83], 0
	s_waitcnt lgkmcnt(6)
	v_mfma_f32_16x16x32_bf16 v[246:249], v[208:211], v[68:71], v[246:249]
	v_mfma_f32_16x16x32_bf16 v[204:207], v[208:211], v[84:87], v[204:207]
	s_waitcnt lgkmcnt(5)
	v_mfma_f32_16x16x32_bf16 v[208:211], v[212:215], v[72:75], v[246:249]
	v_mfma_f32_16x16x32_bf16 v[204:207], v[212:215], v[88:91], v[204:207]
	v_lshlrev_b32_e32 v212, 16, v179
	v_and_b32_e32 v179, 0xffff0000, v179
	s_waitcnt lgkmcnt(4)
	v_mfma_f32_16x16x32_bf16 v[208:211], v[216:219], v[76:79], v[208:211]
	v_mfma_f32_16x16x32_bf16 v[204:207], v[216:219], v[114:117], v[204:207]
	v_pk_mul_f32 v[16:17], v[16:17], s[0:1] op_sel_hi:[1,0]
	v_pk_mul_f32 v[50:51], v[50:51], s[0:1] op_sel_hi:[1,0]
	v_pk_mul_f32 v[48:49], v[48:49], s[0:1] op_sel_hi:[1,0]
	v_pk_mul_f32 v[26:27], v[26:27], s[0:1] op_sel_hi:[1,0]
	s_nop 6
	v_sub_f32_e32 v224, v179, v211
	v_sub_f32_e32 v233, v178, v209
	s_waitcnt vmcnt(11)
	v_lshlrev_b32_e32 v178, 16, v176
	v_and_b32_e32 v176, 0xffff0000, v176
	v_lshlrev_b32_e32 v179, 16, v177
	v_and_b32_e32 v177, 0xffff0000, v177
	v_sub_f32_e32 v225, v212, v210
	v_sub_f32_e32 v203, v203, v208
	v_sub_f32_e32 v246, v177, v207
	v_sub_f32_e32 v247, v179, v206
	v_sub_f32_e32 v248, v176, v205
	v_sub_f32_e32 v249, v178, v204
	ds_read_b128 v[176:179], v101 offset:8192
	ds_read_b128 v[204:207], v101 offset:9216
	ds_read_b128 v[208:211], v101 offset:10240
	ds_read_b128 v[212:215], v101 offset:11264
	s_waitcnt lgkmcnt(7)
	v_mfma_f32_16x16x32_bf16 v[216:219], v[220:223], v[64:67], 0
	v_mfma_f32_16x16x32_bf16 v[220:223], v[220:223], v[80:83], 0
	s_waitcnt lgkmcnt(6)
	v_mfma_f32_16x16x32_bf16 v[216:219], v[234:237], v[68:71], v[216:219]
	v_mfma_f32_16x16x32_bf16 v[220:223], v[234:237], v[84:87], v[220:223]
	v_lshlrev_b32_e32 v234, 16, v174
	v_and_b32_e32 v174, 0xffff0000, v174
	v_lshlrev_b32_e32 v235, 16, v175
	s_waitcnt lgkmcnt(5)
	v_mfma_f32_16x16x32_bf16 v[216:219], v[238:241], v[72:75], v[216:219]
	v_and_b32_e32 v175, 0xffff0000, v175
	v_mfma_f32_16x16x32_bf16 v[220:223], v[238:241], v[88:91], v[220:223]
	s_waitcnt lgkmcnt(4)
	v_mfma_f32_16x16x32_bf16 v[216:219], v[242:245], v[76:79], v[216:219]
	v_mfma_f32_16x16x32_bf16 v[220:223], v[242:245], v[114:117], v[220:223]
	v_pk_mul_f32 v[24:25], v[24:25], s[0:1] op_sel_hi:[1,0]
	v_pk_mul_f32 v[54:55], v[54:55], s[0:1] op_sel_hi:[1,0]
	v_pk_mul_f32 v[52:53], v[52:53], s[0:1] op_sel_hi:[1,0]
	v_pk_mul_f32 v[34:35], v[34:35], s[0:1] op_sel_hi:[1,0]
	s_nop 6
	v_sub_f32_e32 v242, v175, v219
	v_sub_f32_e32 v244, v174, v217
	s_waitcnt vmcnt(10)
	v_lshlrev_b32_e32 v174, 16, v172
	v_and_b32_e32 v172, 0xffff0000, v172
	v_lshlrev_b32_e32 v175, 16, v173
	v_and_b32_e32 v173, 0xffff0000, v173
	v_sub_f32_e32 v243, v235, v218
	v_sub_f32_e32 v245, v234, v216
	v_sub_f32_e32 v250, v173, v223
	v_sub_f32_e32 v251, v175, v222
	v_sub_f32_e32 v227, v172, v221
	v_sub_f32_e32 v182, v174, v220
	ds_read_b128 v[172:175], v101 offset:12288
	ds_read_b128 v[216:219], v101 offset:13312
	ds_read_b128 v[220:223], v101 offset:14336
	ds_read_b128 v[234:237], v101 offset:15360
	s_waitcnt lgkmcnt(7)
	v_mfma_f32_16x16x32_bf16 v[238:241], v[176:179], v[64:67], 0
	v_lshlrev_b32_e32 v183, 16, v170
	v_and_b32_e32 v170, 0xffff0000, v170
	v_mfma_f32_16x16x32_bf16 v[176:179], v[176:179], v[80:83], 0
	s_waitcnt lgkmcnt(6)
	v_mfma_f32_16x16x32_bf16 v[238:241], v[204:207], v[68:71], v[238:241]
	v_mfma_f32_16x16x32_bf16 v[176:179], v[204:207], v[84:87], v[176:179]
	s_waitcnt lgkmcnt(5)
	v_mfma_f32_16x16x32_bf16 v[204:207], v[208:211], v[72:75], v[238:241]
	v_mfma_f32_16x16x32_bf16 v[176:179], v[208:211], v[88:91], v[176:179]
	v_lshlrev_b32_e32 v208, 16, v171
	v_and_b32_e32 v171, 0xffff0000, v171
	s_waitcnt lgkmcnt(4)
	v_mfma_f32_16x16x32_bf16 v[204:207], v[212:215], v[76:79], v[204:207]
	v_mfma_f32_16x16x32_bf16 v[176:179], v[212:215], v[114:117], v[176:179]
	v_pk_mul_f32 v[32:33], v[32:33], s[0:1] op_sel_hi:[1,0]
	v_pk_mul_f32 v[58:59], v[58:59], s[0:1] op_sel_hi:[1,0]
	v_pk_mul_f32 v[56:57], v[56:57], s[0:1] op_sel_hi:[1,0]
	v_mul_f32_e64 v42, v42, s0
	s_nop 6
	v_sub_f32_e32 v207, v171, v207
	v_sub_f32_e32 v205, v170, v205
	s_waitcnt vmcnt(9)
	v_lshlrev_b32_e32 v170, 16, v168
	v_and_b32_e32 v168, 0xffff0000, v168
	v_lshlrev_b32_e32 v171, 16, v169
	v_and_b32_e32 v169, 0xffff0000, v169
	v_sub_f32_e32 v206, v208, v206
	v_sub_f32_e32 v183, v183, v204
	v_sub_f32_e32 v204, v169, v179
	v_sub_f32_e32 v208, v171, v178
	v_sub_f32_e32 v209, v168, v177
	v_sub_f32_e32 v210, v170, v176
	ds_read_b128 v[168:171], v101 offset:49152
	ds_read_b128 v[176:179], v101 offset:50176
	s_waitcnt lgkmcnt(5)
	v_mfma_f32_16x16x32_bf16 v[64:67], v[172:175], v[64:67], 0
	s_waitcnt lgkmcnt(4)
	v_mfma_f32_16x16x32_bf16 v[64:67], v[216:219], v[68:71], v[64:67]
	v_lshlrev_b32_e32 v68, 16, v165
	v_and_b32_e32 v69, 0xffff0000, v165
	v_lshlrev_b32_e32 v70, 16, v164
	s_waitcnt lgkmcnt(3)
	v_mfma_f32_16x16x32_bf16 v[64:67], v[220:223], v[72:75], v[64:67]
	v_and_b32_e32 v71, 0xffff0000, v164
	s_waitcnt vmcnt(8)
	v_lshlrev_b32_e32 v74, 16, v166
	v_and_b32_e32 v75, 0xffff0000, v167
	v_mfma_f32_16x16x32_bf16 v[80:83], v[172:175], v[80:83], 0
	s_waitcnt lgkmcnt(2)
	v_mfma_f32_16x16x32_bf16 v[64:67], v[234:237], v[76:79], v[64:67]
	v_cvt_pk_bf16_f32 v76, v210, v209
	v_cvt_pk_bf16_f32 v77, v208, v204
	s_nop 5
	v_sub_f32_e32 v72, v69, v67
	v_sub_f32_e32 v73, v68, v66
	v_mfma_f32_16x16x32_bf16 v[66:69], v[216:219], v[84:87], v[80:83]
	v_sub_f32_e32 v71, v71, v65
	v_sub_f32_e32 v70, v70, v64
	v_cvt_pk_bf16_f32 v70, v70, v71
	v_mfma_f32_16x16x32_bf16 v[64:67], v[220:223], v[88:91], v[66:69]
	v_cvt_pk_bf16_f32 v71, v73, v72
	v_cvt_pk_bf16_f32 v72, v249, v248
	v_cvt_pk_bf16_f32 v73, v247, v246
	v_mfma_f32_16x16x32_bf16 v[64:67], v[234:237], v[114:117], v[64:67]
	v_mul_f32_e64 v43, v43, s0
	v_pk_mul_f32 v[40:41], v[40:41], s[0:1] op_sel_hi:[1,0]
	v_pk_mul_f32 v[62:63], v[62:63], s[0:1] op_sel_hi:[1,0]
	v_pk_mul_f32 v[60:61], v[60:61], s[0:1] op_sel_hi:[1,0]
	v_and_b32_e32 v68, 0xffff0000, v166
	v_lshlrev_b32_e32 v69, 16, v167
	s_nop 5
	v_sub_f32_e32 v79, v75, v67
	v_sub_f32_e32 v80, v69, v66
	v_sub_f32_e32 v78, v68, v65
	v_sub_f32_e32 v81, v74, v64
	v_cvt_pk_bf16_f32 v64, v203, v233
	v_cvt_pk_bf16_f32 v65, v225, v224
	v_cvt_pk_bf16_f32 v66, v245, v244
	v_cvt_pk_bf16_f32 v67, v243, v242
	v_cvt_pk_bf16_f32 v68, v183, v205
	v_cvt_pk_bf16_f32 v69, v206, v207
	v_cvt_pk_bf16_f32 v74, v182, v227
	v_cvt_pk_bf16_f32 v75, v251, v250
	v_cvt_pk_bf16_f32 v78, v81, v78
	v_cvt_pk_bf16_f32 v79, v80, v79
	ds_read_b128 v[80:83], v101 offset:51200
	ds_read_b128 v[84:87], v101 offset:52224
	ds_read_b128 v[204:207], v101 offset:53248
	ds_read_b128 v[208:211], v101 offset:54272
	s_waitcnt lgkmcnt(5)
	v_mfma_f32_16x16x32_bf16 v[88:91], v[168:171], v[64:67], v[92:95]
	v_mfma_f32_16x16x32_bf16 v[92:95], v[168:171], v[72:75], v[102:105]
	s_waitcnt lgkmcnt(4)
	v_mfma_f32_16x16x32_bf16 v[88:91], v[176:179], v[68:71], v[88:91]
	v_mfma_f32_16x16x32_bf16 v[92:95], v[176:179], v[76:79], v[92:95]
	ds_read_b128 v[212:215], v101 offset:55296
	ds_read_b128 v[216:219], v101 offset:56320
	s_waitcnt lgkmcnt(5)
	v_mfma_f32_16x16x32_bf16 v[106:109], v[80:83], v[64:67], v[106:109]
	v_mfma_f32_16x16x32_bf16 v[80:83], v[80:83], v[72:75], v[110:113]
	s_waitcnt lgkmcnt(4)
	v_mfma_f32_16x16x32_bf16 v[106:109], v[84:87], v[68:71], v[106:109]
	v_mfma_f32_16x16x32_bf16 v[80:83], v[84:87], v[76:79], v[80:83]
	ds_read_b128 v[220:223], v101 offset:32768
	ds_read_b128 v[234:237], v101 offset:33792
	s_waitcnt lgkmcnt(5)
	v_mfma_f32_16x16x32_bf16 v[118:121], v[204:207], v[64:67], v[118:121]
	v_mfma_f32_16x16x32_bf16 v[102:105], v[204:207], v[72:75], v[122:125]
	s_waitcnt lgkmcnt(4)
	v_mfma_f32_16x16x32_bf16 v[118:121], v[208:211], v[68:71], v[118:121]
	v_mfma_f32_16x16x32_bf16 v[102:105], v[208:211], v[76:79], v[102:105]
	ds_read_b128 v[204:207], v101 offset:34816
	ds_read_b128 v[208:211], v101 offset:35840
	s_waitcnt lgkmcnt(5)
	v_mfma_f32_16x16x32_bf16 v[126:129], v[212:215], v[64:67], v[126:129]
	v_mfma_f32_16x16x32_bf16 v[84:87], v[212:215], v[72:75], v[130:133]
	s_waitcnt lgkmcnt(4)
	v_mfma_f32_16x16x32_bf16 v[126:129], v[216:219], v[68:71], v[126:129]
	v_mfma_f32_16x16x32_bf16 v[84:87], v[216:219], v[76:79], v[84:87]
	ds_read_b128 v[212:215], v101 offset:36864
	ds_read_b128 v[216:219], v101 offset:37888
	s_waitcnt lgkmcnt(5)
	v_mfma_f32_16x16x32_bf16 v[0:3], v[220:223], v[64:67], v[0:3]
	v_mfma_f32_16x16x32_bf16 v[114:117], v[220:223], v[72:75], v[20:23]
	s_waitcnt lgkmcnt(4)
	v_mfma_f32_16x16x32_bf16 v[20:23], v[234:237], v[68:71], v[0:3]
	v_mfma_f32_16x16x32_bf16 v[0:3], v[234:237], v[76:79], v[114:117]
	ds_read_b128 v[220:223], v101 offset:38912
	ds_read_b128 v[234:237], v101 offset:39936
	s_waitcnt lgkmcnt(5)
	v_mfma_f32_16x16x32_bf16 v[4:7], v[204:207], v[64:67], v[4:7]
	v_mfma_f32_16x16x32_bf16 v[110:113], v[204:207], v[72:75], v[28:31]
	s_waitcnt lgkmcnt(4)
	v_mfma_f32_16x16x32_bf16 v[28:31], v[208:211], v[68:71], v[4:7]
	v_mfma_f32_16x16x32_bf16 v[4:7], v[208:211], v[76:79], v[110:113]
	ds_read_b128 v[204:207], v101 offset:40960
	ds_read_b128 v[208:211], v101 offset:41984
	s_waitcnt lgkmcnt(5)
	v_mfma_f32_16x16x32_bf16 v[8:11], v[212:215], v[64:67], v[8:11]
	v_mfma_f32_16x16x32_bf16 v[114:117], v[212:215], v[72:75], v[36:39]
	s_waitcnt lgkmcnt(4)
	v_mfma_f32_16x16x32_bf16 v[36:39], v[216:219], v[68:71], v[8:11]
	v_mfma_f32_16x16x32_bf16 v[8:11], v[216:219], v[76:79], v[114:117]
	ds_read_b128 v[212:215], v101 offset:43008
	ds_read_b128 v[216:219], v101 offset:44032
	s_waitcnt lgkmcnt(5)
	v_mfma_f32_16x16x32_bf16 v[12:15], v[220:223], v[64:67], v[12:15]
	v_mfma_f32_16x16x32_bf16 v[110:113], v[220:223], v[72:75], v[44:47]
	s_waitcnt lgkmcnt(4)
	v_mfma_f32_16x16x32_bf16 v[44:47], v[234:237], v[68:71], v[12:15]
	v_mfma_f32_16x16x32_bf16 v[12:15], v[234:237], v[76:79], v[110:113]
	ds_read_b128 v[220:223], v101 offset:45056
	ds_read_b128 v[234:237], v101 offset:46080
	s_waitcnt lgkmcnt(5)
	v_mfma_f32_16x16x32_bf16 v[16:19], v[204:207], v[64:67], v[16:19]
	v_mfma_f32_16x16x32_bf16 v[114:117], v[204:207], v[72:75], v[48:51]
	s_waitcnt lgkmcnt(4)
	v_mfma_f32_16x16x32_bf16 v[48:51], v[208:211], v[68:71], v[16:19]
	v_mfma_f32_16x16x32_bf16 v[16:19], v[208:211], v[76:79], v[114:117]
	ds_read_b128 v[204:207], v101 offset:47104
	ds_read_b128 v[208:211], v101 offset:48128
	s_waitcnt lgkmcnt(5)
	v_mfma_f32_16x16x32_bf16 v[24:27], v[212:215], v[64:67], v[24:27]
	v_mfma_f32_16x16x32_bf16 v[110:113], v[212:215], v[72:75], v[52:55]
	s_waitcnt lgkmcnt(4)
	v_mfma_f32_16x16x32_bf16 v[52:55], v[216:219], v[68:71], v[24:27]
	v_mfma_f32_16x16x32_bf16 v[24:27], v[216:219], v[76:79], v[110:113]
	s_waitcnt lgkmcnt(3)
	v_mfma_f32_16x16x32_bf16 v[32:35], v[220:223], v[64:67], v[32:35]
	v_mfma_f32_16x16x32_bf16 v[114:117], v[220:223], v[72:75], v[56:59]
	s_waitcnt lgkmcnt(2)
	v_mfma_f32_16x16x32_bf16 v[56:59], v[234:237], v[68:71], v[32:35]
	v_mfma_f32_16x16x32_bf16 v[32:35], v[234:237], v[76:79], v[114:117]
	s_waitcnt lgkmcnt(1)
	v_mfma_f32_16x16x32_bf16 v[40:43], v[204:207], v[64:67], v[40:43]
	v_mfma_f32_16x16x32_bf16 v[64:67], v[204:207], v[72:75], v[60:63]
	s_waitcnt lgkmcnt(0)
	v_mfma_f32_16x16x32_bf16 v[60:63], v[208:211], v[68:71], v[40:43]
	v_mfma_f32_16x16x32_bf16 v[40:43], v[208:211], v[76:79], v[64:67]
	s_add_i32 s36, s1, 2
	s_cmp_lt_u32 s1, 62
	s_cselect_b32 s0, s36, s2
	s_lshl_b32 s0, s0, 14
	s_add_u32 s38, s40, s0
	s_waitcnt lgkmcnt(0)
	s_barrier
;     ...
;             BAR_RAW();
; #pragma unroll
;             for (int n = 0; n < 2; ++n)
; #pragma unroll
;                 for (int mt = 0; mt < 4; ++mt)
; #pragma unroll
;                     for (int e = 0; e < 4; ++e) ((LAS float*)(L + OT))[(16 * mt + 4 * g + e) * 132 + 32 * wave + 16 * n + r] = o[n][mt][e];
;             BAR_RAW();
;         }
;         {
;             const int ch = c2 + 1;
;             LAS unsigned char* B0 = L + (ch & 1) * BUF;
;             const int cn = (ch + 1 < 64) ? ch + 1 : ch;
; #pragma unroll
;             for (int n = 0; n < 2; ++n)
; #pragma unroll
;                 for (int mt = 0; mt < 4; ++mt) ua[n][mt] = *(const GAS v2u*)(gu + (size_t)cn * 16384 + (size_t)(((2 * wave + n) * 4 + mt) * 64 + lane) * 8);
;             const float eb = __builtin_bit_cast(float, __builtin_amdgcn_readlane(__builtin_bit_cast(int, ebs), ch));
;             __builtin_amdgcn_sched_barrier(0);
;             bf16x8 Sb[2][4];
; #pragma unroll
;             for (int n = 0; n < 2; ++n)
; #pragma unroll
;                 for (int kb = 0; kb < 4; ++kb) Sb[n][kb] = pack_b(S[n][2 * kb], S[n][2 * kb + 1]);
;             const LAS unsigned char* B0l = B0 + lane * 16;
;             bf16x8 fr0[4], fr1[4];
;             f32x4 o[2][4], vn[2][4]; bf16x8 Vb[2][2];
; #pragma unroll
;             for (int n = 0; n < 2; ++n)
; #pragma unroll
;                 for (int mt = 0; mt < 4; ++mt) o[n][mt] = (f32x4){0.f, 0.f, 0.f, 0.f};
;             if (!(variant & 2)) {
;             fr0[0] = *(const LAS bf16x8*)(B0l + 16384 + 0*1024 + 0*1024); fr0[1] = *(const LAS bf16x8*)(B0l + 16384 + 0*1024 + 1*1024); fr0[2] = *(const LAS bf16x8*)(B0l + 16384 + 0*1024 + 2*1024); fr0[3] = *(const LAS bf16x8*)(B0l + 16384 + 0*1024 + 3*1024);
;             fr1[0] = *(const LAS bf16x8*)(B0l + 16384 + 4*1024 + 0*1024); fr1[1] = *(const LAS bf16x8*)(B0l + 16384 + 4*1024 + 1*1024); fr1[2] = *(const LAS bf16x8*)(B0l + 16384 + 4*1024 + 2*1024); fr1[3] = *(const LAS bf16x8*)(B0l + 16384 + 4*1024 + 3*1024);
;             __builtin_amdgcn_sched_barrier(0);
;             { f32x4 c0 = {0.f, 0.f, 0.f, 0.f}, c1 = {0.f, 0.f, 0.f, 0.f};
;               c0 = MFMA16(fr0[0], Sb[0][0], c0); c1 = MFMA16(fr0[0], Sb[1][0], c1);
;               c0 = MFMA16(fr0[1], Sb[0][1], c0); c1 = MFMA16(fr0[1], Sb[1][1], c1);
;               c0 = MFMA16(fr0[2], Sb[0][2], c0); c1 = MFMA16(fr0[2], Sb[1][2], c1);
	ds_write_b32 v201, v88
	ds_write_b32 v201, v89 offset:528
	ds_write_b32 v201, v90 offset:1056
	ds_write_b32 v202, v91
	ds_write_b32 v201, v106 offset:8448
	ds_write_b32 v201, v107 offset:8976
	ds_write_b32 v201, v108 offset:9504
	ds_write_b32 v201, v109 offset:10032
	ds_write_b32 v201, v118 offset:16896
	ds_write_b32 v201, v119 offset:17424
	ds_write_b32 v201, v120 offset:17952
	ds_write_b32 v201, v121 offset:18480
	ds_write_b32 v201, v126 offset:25344
	ds_write_b32 v201, v127 offset:25872
	ds_write_b32 v201, v128 offset:26400
	ds_write_b32 v201, v129 offset:26928
	ds_write_b32 v201, v92 offset:64
	ds_write_b32 v201, v93 offset:592
	ds_write_b32 v201, v94 offset:1120
	ds_write_b32 v202, v95 offset:64
	ds_write_b32 v201, v80 offset:8512
	ds_write_b32 v201, v81 offset:9040
	ds_write_b32 v201, v82 offset:9568
	ds_write_b32 v201, v83 offset:10096
	ds_write_b32 v201, v102 offset:16960
	ds_write_b32 v201, v103 offset:17488
	ds_write_b32 v201, v104 offset:18016
	ds_write_b32 v201, v105 offset:18544
	ds_write_b32 v201, v84 offset:25408
	ds_write_b32 v201, v85 offset:25936
	ds_write_b32 v201, v86 offset:26464
	ds_write_b32 v201, v87 offset:26992
	s_addc_u32 s39, s41, 0
	s_waitcnt lgkmcnt(0)
	s_barrier
	v_lshl_add_u64 v[64:65], s[38:39], 0, v[98:99]
	v_lshl_add_u64 v[66:67], s[38:39], 0, v[134:135]
	v_lshl_add_u64 v[68:69], s[38:39], 0, v[136:137]
	v_lshl_add_u64 v[70:71], s[38:39], 0, v[138:139]
	global_load_dwordx2 v[178:179], v[64:65], off
	global_load_dwordx2 v[174:175], v[66:67], off
	global_load_dwordx2 v[170:171], v[68:69], off
	global_load_dwordx2 v[164:165], v[70:71], off
	v_lshl_add_u64 v[64:65], s[38:39], 0, v[140:141]
	v_lshl_add_u64 v[66:67], s[38:39], 0, v[142:143]
	v_lshl_add_u64 v[68:69], s[38:39], 0, v[144:145]
	v_lshl_add_u64 v[70:71], s[38:39], 0, v[146:147]
	global_load_dwordx2 v[176:177], v[64:65], off
	global_load_dwordx2 v[172:173], v[66:67], off
	global_load_dwordx2 v[168:169], v[68:69], off
	global_load_dwordx2 v[166:167], v[70:71], off
	s_add_u32 s30, s30, 0x8000
	s_addc_u32 s31, s31, 0
	s_cmp_gt_u32 s1, 61
	ds_read_b128 v[88:91], v200 offset:16384
	ds_read_b128 v[92:95], v200 offset:17408
	ds_read_b128 v[106:109], v200 offset:18432
	ds_read_b128 v[110:113], v200 offset:19456
	ds_read_b128 v[118:121], v200 offset:20480
	ds_read_b128 v[122:125], v200 offset:21504
	ds_read_b128 v[126:129], v200 offset:22528
	ds_read_b128 v[130:133], v200 offset:23552
	v_cvt_pk_bf16_f32 v64, v20, v21
	v_cvt_pk_bf16_f32 v65, v22, v23
	v_cvt_pk_bf16_f32 v66, v28, v29
	v_cvt_pk_bf16_f32 v67, v30, v31
	v_cvt_pk_bf16_f32 v68, v36, v37
	v_cvt_pk_bf16_f32 v69, v38, v39
	v_cvt_pk_bf16_f32 v70, v44, v45
	v_cvt_pk_bf16_f32 v71, v46, v47
	v_cvt_pk_bf16_f32 v72, v48, v49
	v_cvt_pk_bf16_f32 v73, v50, v51
	v_cvt_pk_bf16_f32 v74, v52, v53
	v_cvt_pk_bf16_f32 v75, v54, v55
	v_cvt_pk_bf16_f32 v76, v56, v57
	v_cvt_pk_bf16_f32 v77, v58, v59
	v_cvt_pk_bf16_f32 v78, v60, v61
	v_cvt_pk_bf16_f32 v79, v62, v63
	v_cvt_pk_bf16_f32 v84, v0, v1
	v_cvt_pk_bf16_f32 v85, v2, v3
	v_cvt_pk_bf16_f32 v86, v4, v5
	v_cvt_pk_bf16_f32 v87, v6, v7
	v_cvt_pk_bf16_f32 v80, v8, v9
	v_cvt_pk_bf16_f32 v81, v10, v11
	v_cvt_pk_bf16_f32 v82, v12, v13
	v_cvt_pk_bf16_f32 v83, v14, v15
	v_cvt_pk_bf16_f32 v102, v16, v17
	v_cvt_pk_bf16_f32 v103, v18, v19
	v_cvt_pk_bf16_f32 v104, v24, v25
	v_cvt_pk_bf16_f32 v105, v26, v27
	v_cvt_pk_bf16_f32 v114, v32, v33
	v_cvt_pk_bf16_f32 v115, v34, v35
	v_cvt_pk_bf16_f32 v116, v40, v41
	v_cvt_pk_bf16_f32 v117, v42, v43
	v_readlane_b32 s0, v96, s2
	s_waitcnt lgkmcnt(7)
	v_mfma_f32_16x16x32_bf16 v[204:207], v[88:91], v[64:67], 0
	v_mfma_f32_16x16x32_bf16 v[88:91], v[88:91], v[84:87], 0
	s_waitcnt lgkmcnt(6)
	v_mfma_f32_16x16x32_bf16 v[204:207], v[92:95], v[68:71], v[204:207]
	v_mfma_f32_16x16x32_bf16 v[88:91], v[92:95], v[80:83], v[88:91]
	s_waitcnt lgkmcnt(5)
	v_mfma_f32_16x16x32_bf16 v[92:95], v[106:109], v[72:75], v[204:207]
	v_mfma_f32_16x16x32_bf16 v[106:109], v[106:109], v[102:105], v[88:91]
	s_waitcnt lgkmcnt(4)
	v_mfma_f32_16x16x32_bf16 v[88:91], v[110:113], v[76:79], v[92:95]
	v_mfma_f32_16x16x32_bf16 v[92:95], v[110:113], v[114:117], v[106:109]
	v_pk_mul_f32 v[22:23], v[22:23], s[0:1] op_sel_hi:[1,0]
	v_pk_mul_f32 v[20:21], v[20:21], s[0:1] op_sel_hi:[1,0]
	v_pk_mul_f32 v[2:3], v[2:3], s[0:1] op_sel_hi:[1,0]
	v_pk_mul_f32 v[0:1], v[0:1], s[0:1] op_sel_hi:[1,0]
	v_pk_mul_f32 v[30:31], v[30:31], s[0:1] op_sel_hi:[1,0]
	s_nop 0
	ds_read_b128 v[204:207], v200 offset:24576
	ds_read_b128 v[208:211], v200 offset:25600
	ds_read_b128 v[212:215], v200 offset:26624
	ds_read_b128 v[216:219], v200 offset:27648
	s_waitcnt lgkmcnt(7)
	v_mfma_f32_16x16x32_bf16 v[106:109], v[118:121], v[64:67], 0
	v_mfma_f32_16x16x32_bf16 v[110:113], v[118:121], v[84:87], 0
	s_waitcnt lgkmcnt(6)
	v_mfma_f32_16x16x32_bf16 v[106:109], v[122:125], v[68:71], v[106:109]
	v_mfma_f32_16x16x32_bf16 v[110:113], v[122:125], v[80:83], v[110:113]
	s_waitcnt lgkmcnt(5)
	v_mfma_f32_16x16x32_bf16 v[106:109], v[126:129], v[72:75], v[106:109]
	v_mfma_f32_16x16x32_bf16 v[110:113], v[126:129], v[102:105], v[110:113]
	s_waitcnt lgkmcnt(4)
	v_mfma_f32_16x16x32_bf16 v[106:109], v[130:133], v[76:79], v[106:109]
	v_mfma_f32_16x16x32_bf16 v[110:113], v[130:133], v[114:117], v[110:113]
	v_pk_mul_f32 v[28:29], v[28:29], s[0:1] op_sel_hi:[1,0]
	v_pk_mul_f32 v[6:7], v[6:7], s[0:1] op_sel_hi:[1,0]
	v_pk_mul_f32 v[4:5], v[4:5], s[0:1] op_sel_hi:[1,0]
	v_pk_mul_f32 v[38:39], v[38:39], s[0:1] op_sel_hi:[1,0]
	ds_read_b128 v[126:129], v200 offset:28672
	ds_read_b128 v[130:133], v200 offset:29696
	ds_read_b128 v[220:223], v200 offset:30720
	ds_read_b128 v[234:237], v200 offset:31744
	s_waitcnt lgkmcnt(7)
;     ...
;             fr0[0] = *(const LAS bf16x8*)(B0l + 16384 + 8*1024 + 0*1024); fr0[1] = *(const LAS bf16x8*)(B0l + 16384 + 8*1024 + 1*1024); fr0[2] = *(const LAS bf16x8*)(B0l + 16384 + 8*1024 + 2*1024); fr0[3] = *(const LAS bf16x8*)(B0l + 16384 + 8*1024 + 3*1024);
;             __builtin_amdgcn_sched_barrier(0);
;             { f32x4 c0 = {0.f, 0.f, 0.f, 0.f}, c1 = {0.f, 0.f, 0.f, 0.f};
;               c0 = MFMA16(fr1[0], Sb[0][0], c0); c1 = MFMA16(fr1[0], Sb[1][0], c1);
;               c0 = MFMA16(fr1[1], Sb[0][1], c0); c1 = MFMA16(fr1[1], Sb[1][1], c1);
;               c0 = MFMA16(fr1[2], Sb[0][2], c0); c1 = MFMA16(fr1[2], Sb[1][2], c1);
;               c0 = MFMA16(fr1[3], Sb[0][3], c0); c1 = MFMA16(fr1[3], Sb[1][3], c1);
;               o[0][1] = c0; o[1][1] = c1; }
;             __builtin_amdgcn_sched_barrier(0);
;             fr1[0] = *(const LAS bf16x8*)(B0l + 16384 + 12*1024 + 0*1024); fr1[1] = *(const LAS bf16x8*)(B0l + 16384 + 12*1024 + 1*1024); fr1[2] = *(const LAS bf16x8*)(B0l + 16384 + 12*1024 + 2*1024); fr1[3] = *(const LAS bf16x8*)(B0l + 16384 + 12*1024 + 3*1024);
;             __builtin_amdgcn_sched_barrier(0);
;             { f32x4 c0 = {0.f, 0.f, 0.f, 0.f}, c1 = {0.f, 0.f, 0.f, 0.f};
;               c0 = MFMA16(fr0[0], Sb[0][0], c0); c1 = MFMA16(fr0[0], Sb[1][0], c1);
;               c0 = MFMA16(fr0[1], Sb[0][1], c0); c1 = MFMA16(fr0[1], Sb[1][1], c1);
;               c0 = MFMA16(fr0[2], Sb[0][2], c0); c1 = MFMA16(fr0[2], Sb[1][2], c1);
;               c0 = MFMA16(fr0[3], Sb[0][3], c0); c1 = MFMA16(fr0[3], Sb[1][3], c1);
;               o[0][2] = c0; o[1][2] = c1; }
;             __builtin_amdgcn_sched_barrier(0);
;             fr0[0] = *(const LAS bf16x8*)(B0l + 0*1024 + 0*1024); fr0[1] = *(const LAS bf16x8*)(B0l + 0*1024 + 1*1024); fr0[2] = *(const LAS bf16x8*)(B0l + 0*1024 + 2*1024); fr0[3] = *(const LAS bf16x8*)(B0l + 0*1024 + 3*1024);
;             __builtin_amdgcn_sched_barrier(0);
;             { f32x4 c0 = {0.f, 0.f, 0.f, 0.f}, c1 = {0.f, 0.f, 0.f, 0.f};
;               c0 = MFMA16(fr1[0], Sb[0][0], c0); c1 = MFMA16(fr1[0], Sb[1][0], c1);
;               c0 = MFMA16(fr1[1], Sb[0][1], c0); c1 = MFMA16(fr1[1], Sb[1][1], c1);
;               c0 = MFMA16(fr1[2], Sb[0][2], c0); c1 = MFMA16(fr1[2], Sb[1][2], c1);
;               c0 = MFMA16(fr1[3], Sb[0][3], c0); c1 = MFMA16(fr1[3], Sb[1][3], c1);
	v_mfma_f32_16x16x32_bf16 v[118:121], v[204:207], v[64:67], 0
	v_mfma_f32_16x16x32_bf16 v[122:125], v[204:207], v[84:87], 0
	s_waitcnt lgkmcnt(6)
	v_mfma_f32_16x16x32_bf16 v[118:121], v[208:211], v[68:71], v[118:121]
	v_mfma_f32_16x16x32_bf16 v[122:125], v[208:211], v[80:83], v[122:125]
	s_waitcnt lgkmcnt(5)
	v_mfma_f32_16x16x32_bf16 v[118:121], v[212:215], v[72:75], v[118:121]
	v_mfma_f32_16x16x32_bf16 v[122:125], v[212:215], v[102:105], v[122:125]
	s_waitcnt lgkmcnt(4)
	v_mfma_f32_16x16x32_bf16 v[118:121], v[216:219], v[76:79], v[118:121]
	v_mfma_f32_16x16x32_bf16 v[122:125], v[216:219], v[114:117], v[122:125]
	v_pk_mul_f32 v[36:37], v[36:37], s[0:1] op_sel_hi:[1,0]
	v_pk_mul_f32 v[10:11], v[10:11], s[0:1] op_sel_hi:[1,0]
	v_pk_mul_f32 v[8:9], v[8:9], s[0:1] op_sel_hi:[1,0]
	v_pk_mul_f32 v[46:47], v[46:47], s[0:1] op_sel_hi:[1,0]
	ds_read_b128 v[204:207], v101 offset:57344
	ds_read_b128 v[208:211], v101 offset:58368
	ds_read_b128 v[212:215], v101 offset:59392
	ds_read_b128 v[216:219], v101 offset:60416
	s_waitcnt lgkmcnt(7)
	v_mfma_f32_16x16x32_bf16 v[238:241], v[126:129], v[64:67], 0
	v_mfma_f32_16x16x32_bf16 v[126:129], v[126:129], v[84:87], 0
	s_waitcnt lgkmcnt(6)
	v_mfma_f32_16x16x32_bf16 v[238:241], v[130:133], v[68:71], v[238:241]
	v_mfma_f32_16x16x32_bf16 v[126:129], v[130:133], v[80:83], v[126:129]
	s_waitcnt lgkmcnt(5)
	v_mfma_f32_16x16x32_bf16 v[130:133], v[220:223], v[72:75], v[238:241]
	v_mfma_f32_16x16x32_bf16 v[220:223], v[220:223], v[102:105], v[126:129]
	s_waitcnt lgkmcnt(4)
	v_mfma_f32_16x16x32_bf16 v[126:129], v[234:237], v[76:79], v[130:133]
	v_mfma_f32_16x16x32_bf16 v[130:133], v[234:237], v[114:117], v[220:223]
	v_pk_mul_f32 v[44:45], v[44:45], s[0:1] op_sel_hi:[1,0]
	v_pk_mul_f32 v[14:15], v[14:15], s[0:1] op_sel_hi:[1,0]
	v_pk_mul_f32 v[12:13], v[12:13], s[0:1] op_sel_hi:[1,0]
	v_pk_mul_f32 v[50:51], v[50:51], s[0:1] op_sel_hi:[1,0]
	s_nop 4
	ds_read_b128 v[220:223], v101 offset:61440
	ds_read_b128 v[234:237], v101 offset:62464
	ds_read_b128 v[238:241], v101 offset:63488
	ds_read_b128 v[242:245], v101 offset:64512
	s_waitcnt lgkmcnt(7)
	v_mfma_f32_16x16x32_bf16 v[246:249], v[204:207], v[64:67], 0
	s_waitcnt vmcnt(15)
	v_lshlrev_b32_e32 v182, 16, v198
	v_and_b32_e32 v183, 0xffff0000, v198
	v_lshlrev_b32_e32 v198, 16, v199
	v_mfma_f32_16x16x32_bf16 v[204:207], v[204:207], v[84:87], 0
	v_and_b32_e32 v199, 0xffff0000, v199
	s_waitcnt lgkmcnt(6)
	v_mfma_f32_16x16x32_bf16 v[246:249], v[208:211], v[68:71], v[246:249]
	v_mfma_f32_16x16x32_bf16 v[204:207], v[208:211], v[80:83], v[204:207]
	s_waitcnt lgkmcnt(5)
	v_mfma_f32_16x16x32_bf16 v[208:211], v[212:215], v[72:75], v[246:249]
	v_mfma_f32_16x16x32_bf16 v[204:207], v[212:215], v[102:105], v[204:207]
	s_waitcnt lgkmcnt(4)
	v_mfma_f32_16x16x32_bf16 v[208:211], v[216:219], v[76:79], v[208:211]
	v_mfma_f32_16x16x32_bf16 v[204:207], v[216:219], v[114:117], v[204:207]
	v_pk_mul_f32 v[48:49], v[48:49], s[0:1] op_sel_hi:[1,0]
	v_pk_mul_f32 v[18:19], v[18:19], s[0:1] op_sel_hi:[1,0]
	v_pk_mul_f32 v[16:17], v[16:17], s[0:1] op_sel_hi:[1,0]
	v_pk_mul_f32 v[54:55], v[54:55], s[0:1] op_sel_hi:[1,0]
	s_nop 6
	v_sub_f32_e32 v203, v199, v211
	v_sub_f32_e32 v224, v198, v210
	s_waitcnt vmcnt(11)
	v_lshlrev_b32_e32 v198, 16, v196
	v_and_b32_e32 v196, 0xffff0000, v196
	v_lshlrev_b32_e32 v199, 16, v197
	v_and_b32_e32 v197, 0xffff0000, v197
	v_sub_f32_e32 v183, v183, v209
	v_sub_f32_e32 v182, v182, v208
	v_sub_f32_e32 v225, v197, v207
	v_sub_f32_e32 v227, v199, v206
	v_sub_f32_e32 v233, v196, v205
	v_sub_f32_e32 v246, v198, v204
	ds_read_b128 v[196:199], v200 offset:8192
	ds_read_b128 v[204:207], v200 offset:9216
	ds_read_b128 v[208:211], v200 offset:10240
	ds_read_b128 v[212:215], v200 offset:11264
	s_waitcnt lgkmcnt(7)
	v_mfma_f32_16x16x32_bf16 v[216:219], v[220:223], v[64:67], 0
	v_mfma_f32_16x16x32_bf16 v[220:223], v[220:223], v[84:87], 0
	s_waitcnt lgkmcnt(6)
	v_mfma_f32_16x16x32_bf16 v[216:219], v[234:237], v[68:71], v[216:219]
	v_mfma_f32_16x16x32_bf16 v[220:223], v[234:237], v[80:83], v[220:223]
	v_lshlrev_b32_e32 v234, 16, v194
	v_and_b32_e32 v194, 0xffff0000, v194
	v_lshlrev_b32_e32 v235, 16, v195
	s_waitcnt lgkmcnt(5)
	v_mfma_f32_16x16x32_bf16 v[216:219], v[238:241], v[72:75], v[216:219]
	v_and_b32_e32 v195, 0xffff0000, v195
	v_mfma_f32_16x16x32_bf16 v[220:223], v[238:241], v[102:105], v[220:223]
	s_waitcnt lgkmcnt(4)
	v_mfma_f32_16x16x32_bf16 v[216:219], v[242:245], v[76:79], v[216:219]
	v_mfma_f32_16x16x32_bf16 v[220:223], v[242:245], v[114:117], v[220:223]
	v_pk_mul_f32 v[52:53], v[52:53], s[0:1] op_sel_hi:[1,0]
	v_pk_mul_f32 v[26:27], v[26:27], s[0:1] op_sel_hi:[1,0]
	v_pk_mul_f32 v[24:25], v[24:25], s[0:1] op_sel_hi:[1,0]
	v_pk_mul_f32 v[58:59], v[58:59], s[0:1] op_sel_hi:[1,0]
	s_nop 6
	v_sub_f32_e32 v242, v195, v219
	v_sub_f32_e32 v244, v194, v217
	s_waitcnt vmcnt(10)
	v_lshlrev_b32_e32 v194, 16, v192
	v_and_b32_e32 v192, 0xffff0000, v192
	v_lshlrev_b32_e32 v195, 16, v193
	v_and_b32_e32 v193, 0xffff0000, v193
	v_sub_f32_e32 v243, v235, v218
	v_sub_f32_e32 v245, v234, v216
	v_sub_f32_e32 v247, v193, v223
	v_sub_f32_e32 v248, v195, v222
	v_sub_f32_e32 v249, v192, v221
	v_sub_f32_e32 v250, v194, v220
	ds_read_b128 v[192:195], v200 offset:12288
	ds_read_b128 v[216:219], v200 offset:13312
	ds_read_b128 v[220:223], v200 offset:14336
	ds_read_b128 v[234:237], v200 offset:15360
	s_waitcnt lgkmcnt(7)
	v_mfma_f32_16x16x32_bf16 v[238:241], v[196:199], v[64:67], 0
	v_mfma_f32_16x16x32_bf16 v[196:199], v[196:199], v[84:87], 0
	s_waitcnt lgkmcnt(6)
	v_mfma_f32_16x16x32_bf16 v[238:241], v[204:207], v[68:71], v[238:241]
	v_mfma_f32_16x16x32_bf16 v[196:199], v[204:207], v[80:83], v[196:199]
	s_waitcnt lgkmcnt(5)
;     ...
;             fr1[0] = *(const LAS bf16x8*)(B0l + 12*1024 + 0*1024); fr1[1] = *(const LAS bf16x8*)(B0l + 12*1024 + 1*1024); fr1[2] = *(const LAS bf16x8*)(B0l + 12*1024 + 2*1024); fr1[3] = *(const LAS bf16x8*)(B0l + 12*1024 + 3*1024);
;             __builtin_amdgcn_sched_barrier(0);
;             { f32x4 a0 = {0.f, 0.f, 0.f, 0.f}, a1 = {0.f, 0.f, 0.f, 0.f};
;               a0 = MFMA16(fr0[0], Sb[0][0], a0); a1 = MFMA16(fr0[0], Sb[1][0], a1);
;               a0 = MFMA16(fr0[1], Sb[0][1], a0); a1 = MFMA16(fr0[1], Sb[1][1], a1);
;               a0 = MFMA16(fr0[2], Sb[0][2], a0); a1 = MFMA16(fr0[2], Sb[1][2], a1);
;               a0 = MFMA16(fr0[3], Sb[0][3], a0); a1 = MFMA16(fr0[3], Sb[1][3], a1);
;               vn[0][2] = (f32x4){bflo(ua[0][2].x), bfhi(ua[0][2].x), bflo(ua[0][2].y), bfhi(ua[0][2].y)} - a0; vn[1][2] = (f32x4){bflo(ua[1][2].x), bfhi(ua[1][2].x), bflo(ua[1][2].y), bfhi(ua[1][2].y)} - a1; }
;             __builtin_amdgcn_sched_barrier(0);
;             fr0[0] = *(const LAS bf16x8*)(B0l + 49152 + 0*1024 + 0*1024); fr0[1] = *(const LAS bf16x8*)(B0l + 49152 + 0*1024 + 1*1024);
;             __builtin_amdgcn_sched_barrier(0);
;             { f32x4 a0 = {0.f, 0.f, 0.f, 0.f}, a1 = {0.f, 0.f, 0.f, 0.f};
;               a0 = MFMA16(fr1[0], Sb[0][0], a0); a1 = MFMA16(fr1[0], Sb[1][0], a1);
;               a0 = MFMA16(fr1[1], Sb[0][1], a0); a1 = MFMA16(fr1[1], Sb[1][1], a1);
;               a0 = MFMA16(fr1[2], Sb[0][2], a0); a1 = MFMA16(fr1[2], Sb[1][2], a1);
;               a0 = MFMA16(fr1[3], Sb[0][3], a0); a1 = MFMA16(fr1[3], Sb[1][3], a1);
;               vn[0][3] = (f32x4){bflo(ua[0][3].x), bfhi(ua[0][3].x), bflo(ua[0][3].y), bfhi(ua[0][3].y)} - a0; vn[1][3] = (f32x4){bflo(ua[1][3].x), bfhi(ua[1][3].x), bflo(ua[1][3].y), bfhi(ua[1][3].y)} - a1; }
;             Vb[0][0] = pack_b(vn[0][0], vn[0][1]); Vb[0][1] = pack_b(vn[0][2], vn[0][3]); Vb[1][0] = pack_b(vn[1][0], vn[1][1]); Vb[1][1] = pack_b(vn[1][2], vn[1][3]);
;             __builtin_amdgcn_sched_barrier(0);
;             fr1[0] = *(const LAS bf16x8*)(B0l + 49152 + 2*1024 + 0*1024); fr1[1] = *(const LAS bf16x8*)(B0l + 49152 + 2*1024 + 1*1024);
;             __builtin_amdgcn_sched_barrier(0);
;             o[0][0] = MFMA16(fr0[0], Vb[0][0], o[0][0]); o[1][0] = MFMA16(fr0[0], Vb[1][0], o[1][0]);
;             o[0][0] = MFMA16(fr0[1], Vb[0][1], o[0][0]); o[1][0] = MFMA16(fr0[1], Vb[1][1], o[1][0]);
	v_mfma_f32_16x16x32_bf16 v[204:207], v[208:211], v[72:75], v[238:241]
	v_mfma_f32_16x16x32_bf16 v[196:199], v[208:211], v[102:105], v[196:199]
	v_lshlrev_b32_e32 v208, 16, v190
	v_and_b32_e32 v190, 0xffff0000, v190
	v_lshlrev_b32_e32 v209, 16, v191
	s_waitcnt lgkmcnt(4)
	v_mfma_f32_16x16x32_bf16 v[204:207], v[212:215], v[76:79], v[204:207]
	v_and_b32_e32 v191, 0xffff0000, v191
	v_mfma_f32_16x16x32_bf16 v[196:199], v[212:215], v[114:117], v[196:199]
	v_pk_mul_f32 v[56:57], v[56:57], s[0:1] op_sel_hi:[1,0]
	v_pk_mul_f32 v[34:35], v[34:35], s[0:1] op_sel_hi:[1,0]
	v_pk_mul_f32 v[32:33], v[32:33], s[0:1] op_sel_hi:[1,0]
	v_mul_f32_e64 v62, v62, s0
	s_nop 5
	v_sub_f32_e32 v207, v191, v207
	v_sub_f32_e32 v205, v190, v205
	s_waitcnt vmcnt(9)
	v_lshlrev_b32_e32 v190, 16, v188
	v_and_b32_e32 v188, 0xffff0000, v188
	v_lshlrev_b32_e32 v191, 16, v189
	v_and_b32_e32 v189, 0xffff0000, v189
	v_sub_f32_e32 v206, v209, v206
	v_sub_f32_e32 v204, v208, v204
	v_sub_f32_e32 v208, v189, v199
	v_sub_f32_e32 v209, v191, v198
	v_sub_f32_e32 v210, v188, v197
	v_sub_f32_e32 v211, v190, v196
	ds_read_b128 v[188:191], v200 offset:49152
	ds_read_b128 v[196:199], v200 offset:50176
	s_waitcnt lgkmcnt(5)
	v_mfma_f32_16x16x32_bf16 v[64:67], v[192:195], v[64:67], 0
	s_waitcnt lgkmcnt(4)
	v_mfma_f32_16x16x32_bf16 v[64:67], v[216:219], v[68:71], v[64:67]
	v_lshlrev_b32_e32 v68, 16, v181
	v_and_b32_e32 v69, 0xffff0000, v181
	v_lshlrev_b32_e32 v70, 16, v180
	s_waitcnt lgkmcnt(3)
	v_mfma_f32_16x16x32_bf16 v[64:67], v[220:223], v[72:75], v[64:67]
	v_and_b32_e32 v71, 0xffff0000, v180
	s_waitcnt vmcnt(8)
	v_lshlrev_b32_e32 v74, 16, v186
	v_and_b32_e32 v75, 0xffff0000, v187
	v_mfma_f32_16x16x32_bf16 v[84:87], v[192:195], v[84:87], 0
	s_waitcnt lgkmcnt(2)
	v_mfma_f32_16x16x32_bf16 v[64:67], v[234:237], v[76:79], v[64:67]
	v_cvt_pk_bf16_f32 v76, v211, v210
	v_cvt_pk_bf16_f32 v77, v209, v208
	s_nop 5
	v_sub_f32_e32 v72, v69, v67
	v_sub_f32_e32 v73, v68, v66
	v_mfma_f32_16x16x32_bf16 v[66:69], v[216:219], v[80:83], v[84:87]
	v_sub_f32_e32 v71, v71, v65
	v_sub_f32_e32 v70, v70, v64
	v_cvt_pk_bf16_f32 v70, v70, v71
	v_mfma_f32_16x16x32_bf16 v[64:67], v[220:223], v[102:105], v[66:69]
	v_cvt_pk_bf16_f32 v71, v73, v72
	v_cvt_pk_bf16_f32 v72, v246, v233
	v_cvt_pk_bf16_f32 v73, v227, v225
	v_mfma_f32_16x16x32_bf16 v[64:67], v[234:237], v[114:117], v[64:67]
	v_mul_f32_e64 v63, v63, s0
	v_pk_mul_f32 v[60:61], v[60:61], s[0:1] op_sel_hi:[1,0]
	v_pk_mul_f32 v[42:43], v[42:43], s[0:1] op_sel_hi:[1,0]
	v_pk_mul_f32 v[40:41], v[40:41], s[0:1] op_sel_hi:[1,0]
	v_and_b32_e32 v68, 0xffff0000, v186
	v_lshlrev_b32_e32 v69, 16, v187
	s_nop 5
	v_sub_f32_e32 v79, v75, v67
	v_sub_f32_e32 v80, v69, v66
	v_sub_f32_e32 v78, v68, v65
	v_sub_f32_e32 v81, v74, v64
	v_cvt_pk_bf16_f32 v64, v182, v183
	v_cvt_pk_bf16_f32 v65, v224, v203
	v_cvt_pk_bf16_f32 v66, v245, v244
	v_cvt_pk_bf16_f32 v67, v243, v242
	v_cvt_pk_bf16_f32 v68, v204, v205
	v_cvt_pk_bf16_f32 v69, v206, v207
	v_cvt_pk_bf16_f32 v74, v250, v249
	v_cvt_pk_bf16_f32 v75, v248, v247
	v_cvt_pk_bf16_f32 v78, v81, v78
	v_cvt_pk_bf16_f32 v79, v80, v79
	ds_read_b128 v[80:83], v200 offset:51200
	ds_read_b128 v[84:87], v200 offset:52224
	ds_read_b128 v[204:207], v200 offset:53248
	ds_read_b128 v[208:211], v200 offset:54272
	s_waitcnt lgkmcnt(5)
	v_mfma_f32_16x16x32_bf16 v[88:91], v[188:191], v[64:67], v[88:91]
	v_mfma_f32_16x16x32_bf16 v[92:95], v[188:191], v[72:75], v[92:95]
	s_waitcnt lgkmcnt(4)
	v_mfma_f32_16x16x32_bf16 v[88:91], v[196:199], v[68:71], v[88:91]
	v_mfma_f32_16x16x32_bf16 v[92:95], v[196:199], v[76:79], v[92:95]
	ds_read_b128 v[212:215], v200 offset:55296
	ds_read_b128 v[216:219], v200 offset:56320
	s_waitcnt lgkmcnt(5)
	v_mfma_f32_16x16x32_bf16 v[106:109], v[80:83], v[64:67], v[106:109]
	v_mfma_f32_16x16x32_bf16 v[80:83], v[80:83], v[72:75], v[110:113]
	s_waitcnt lgkmcnt(4)
	v_mfma_f32_16x16x32_bf16 v[106:109], v[84:87], v[68:71], v[106:109]
	v_mfma_f32_16x16x32_bf16 v[80:83], v[84:87], v[76:79], v[80:83]
	ds_read_b128 v[220:223], v200 offset:32768
	ds_read_b128 v[234:237], v200 offset:33792
	s_waitcnt lgkmcnt(5)
	v_mfma_f32_16x16x32_bf16 v[118:121], v[204:207], v[64:67], v[118:121]
	v_mfma_f32_16x16x32_bf16 v[102:105], v[204:207], v[72:75], v[122:125]
	s_waitcnt lgkmcnt(4)
	v_mfma_f32_16x16x32_bf16 v[118:121], v[208:211], v[68:71], v[118:121]
	v_mfma_f32_16x16x32_bf16 v[102:105], v[208:211], v[76:79], v[102:105]
	ds_read_b128 v[204:207], v200 offset:34816
	ds_read_b128 v[208:211], v200 offset:35840
	s_waitcnt lgkmcnt(5)
	v_mfma_f32_16x16x32_bf16 v[126:129], v[212:215], v[64:67], v[126:129]
	v_mfma_f32_16x16x32_bf16 v[84:87], v[212:215], v[72:75], v[130:133]
	s_waitcnt lgkmcnt(4)
;     ...
;             { f32x4 a0 = S[0][3] * eb, a1 = S[1][3] * eb;
;               a0 = MFMA16(fr1[0], Vb[0][0], a0); a1 = MFMA16(fr1[0], Vb[1][0], a1);
;               a0 = MFMA16(fr1[1], Vb[0][1], a0); a1 = MFMA16(fr1[1], Vb[1][1], a1);
;               S[0][3] = a0; S[1][3] = a1; }
;             __builtin_amdgcn_sched_barrier(0);
;             fr1[0] = *(const LAS bf16x8*)(B0l + 32768 + 10*1024 + 0*1024); fr1[1] = *(const LAS bf16x8*)(B0l + 32768 + 10*1024 + 1*1024);
;             __builtin_amdgcn_sched_barrier(0);
;             { f32x4 a0 = S[0][4] * eb, a1 = S[1][4] * eb;
;               a0 = MFMA16(fr0[0], Vb[0][0], a0); a1 = MFMA16(fr0[0], Vb[1][0], a1);
;               a0 = MFMA16(fr0[1], Vb[0][1], a0); a1 = MFMA16(fr0[1], Vb[1][1], a1);
;               S[0][4] = a0; S[1][4] = a1; }
;             __builtin_amdgcn_sched_barrier(0);
;             fr0[0] = *(const LAS bf16x8*)(B0l + 32768 + 12*1024 + 0*1024); fr0[1] = *(const LAS bf16x8*)(B0l + 32768 + 12*1024 + 1*1024);
;             __builtin_amdgcn_sched_barrier(0);
;             { f32x4 a0 = S[0][5] * eb, a1 = S[1][5] * eb;
;               a0 = MFMA16(fr1[0], Vb[0][0], a0); a1 = MFMA16(fr1[0], Vb[1][0], a1);
;               a0 = MFMA16(fr1[1], Vb[0][1], a0); a1 = MFMA16(fr1[1], Vb[1][1], a1);
;               S[0][5] = a0; S[1][5] = a1; }
;             __builtin_amdgcn_sched_barrier(0);
;             fr1[0] = *(const LAS bf16x8*)(B0l + 32768 + 14*1024 + 0*1024); fr1[1] = *(const LAS bf16x8*)(B0l + 32768 + 14*1024 + 1*1024);
;             __builtin_amdgcn_sched_barrier(0);
;             { f32x4 a0 = S[0][6] * eb, a1 = S[1][6] * eb;
;               a0 = MFMA16(fr0[0], Vb[0][0], a0); a1 = MFMA16(fr0[0], Vb[1][0], a1);
;               a0 = MFMA16(fr0[1], Vb[0][1], a0); a1 = MFMA16(fr0[1], Vb[1][1], a1);
;               S[0][6] = a0; S[1][6] = a1; }
;             __builtin_amdgcn_sched_barrier(0);
;             __builtin_amdgcn_sched_barrier(0);
;             { f32x4 a0 = S[0][7] * eb, a1 = S[1][7] * eb;
;               a0 = MFMA16(fr1[0], Vb[0][0], a0); a1 = MFMA16(fr1[0], Vb[1][0], a1);
;               a0 = MFMA16(fr1[1], Vb[0][1], a0); a1 = MFMA16(fr1[1], Vb[1][1], a1);
;               S[0][7] = a0; S[1][7] = a1; }
;             __builtin_amdgcn_sched_barrier(0);
;             }
;             BAR_RAW();
; #pragma unroll
;             for (int n = 0; n < 2; ++n)
; #pragma unroll
	v_mfma_f32_16x16x32_bf16 v[126:129], v[216:219], v[68:71], v[126:129]
	v_mfma_f32_16x16x32_bf16 v[84:87], v[216:219], v[76:79], v[84:87]
	ds_read_b128 v[212:215], v200 offset:36864
	ds_read_b128 v[216:219], v200 offset:37888
	s_waitcnt lgkmcnt(5)
	v_mfma_f32_16x16x32_bf16 v[20:23], v[220:223], v[64:67], v[20:23]
	v_mfma_f32_16x16x32_bf16 v[114:117], v[220:223], v[72:75], v[0:3]
	s_waitcnt lgkmcnt(4)
	v_mfma_f32_16x16x32_bf16 v[0:3], v[234:237], v[68:71], v[20:23]
	v_mfma_f32_16x16x32_bf16 v[20:23], v[234:237], v[76:79], v[114:117]
	ds_read_b128 v[220:223], v200 offset:38912
	ds_read_b128 v[234:237], v200 offset:39936
	s_waitcnt lgkmcnt(5)
	v_mfma_f32_16x16x32_bf16 v[28:31], v[204:207], v[64:67], v[28:31]
	v_mfma_f32_16x16x32_bf16 v[110:113], v[204:207], v[72:75], v[4:7]
	s_waitcnt lgkmcnt(4)
	v_mfma_f32_16x16x32_bf16 v[4:7], v[208:211], v[68:71], v[28:31]
	v_mfma_f32_16x16x32_bf16 v[28:31], v[208:211], v[76:79], v[110:113]
	ds_read_b128 v[204:207], v200 offset:40960
	ds_read_b128 v[208:211], v200 offset:41984
	s_waitcnt lgkmcnt(5)
	v_mfma_f32_16x16x32_bf16 v[36:39], v[212:215], v[64:67], v[36:39]
	v_mfma_f32_16x16x32_bf16 v[114:117], v[212:215], v[72:75], v[8:11]
	s_waitcnt lgkmcnt(4)
	v_mfma_f32_16x16x32_bf16 v[8:11], v[216:219], v[68:71], v[36:39]
	v_mfma_f32_16x16x32_bf16 v[36:39], v[216:219], v[76:79], v[114:117]
	ds_read_b128 v[212:215], v200 offset:43008
	ds_read_b128 v[216:219], v200 offset:44032
	s_waitcnt lgkmcnt(5)
	v_mfma_f32_16x16x32_bf16 v[44:47], v[220:223], v[64:67], v[44:47]
	v_mfma_f32_16x16x32_bf16 v[110:113], v[220:223], v[72:75], v[12:15]
	s_waitcnt lgkmcnt(4)
	v_mfma_f32_16x16x32_bf16 v[12:15], v[234:237], v[68:71], v[44:47]
	v_mfma_f32_16x16x32_bf16 v[44:47], v[234:237], v[76:79], v[110:113]
	ds_read_b128 v[220:223], v200 offset:45056
	ds_read_b128 v[234:237], v200 offset:46080
	s_waitcnt lgkmcnt(5)
	v_mfma_f32_16x16x32_bf16 v[48:51], v[204:207], v[64:67], v[48:51]
	v_mfma_f32_16x16x32_bf16 v[114:117], v[204:207], v[72:75], v[16:19]
	s_waitcnt lgkmcnt(4)
	v_mfma_f32_16x16x32_bf16 v[16:19], v[208:211], v[68:71], v[48:51]
	v_mfma_f32_16x16x32_bf16 v[48:51], v[208:211], v[76:79], v[114:117]
	ds_read_b128 v[204:207], v200 offset:47104
	ds_read_b128 v[208:211], v200 offset:48128
	s_waitcnt lgkmcnt(5)
	v_mfma_f32_16x16x32_bf16 v[52:55], v[212:215], v[64:67], v[52:55]
	v_mfma_f32_16x16x32_bf16 v[110:113], v[212:215], v[72:75], v[24:27]
	s_waitcnt lgkmcnt(4)
	v_mfma_f32_16x16x32_bf16 v[24:27], v[216:219], v[68:71], v[52:55]
	v_mfma_f32_16x16x32_bf16 v[52:55], v[216:219], v[76:79], v[110:113]
	s_waitcnt lgkmcnt(3)
	v_mfma_f32_16x16x32_bf16 v[56:59], v[220:223], v[64:67], v[56:59]
	v_mfma_f32_16x16x32_bf16 v[114:117], v[220:223], v[72:75], v[32:35]
	s_waitcnt lgkmcnt(2)
	v_mfma_f32_16x16x32_bf16 v[32:35], v[234:237], v[68:71], v[56:59]
	v_mfma_f32_16x16x32_bf16 v[56:59], v[234:237], v[76:79], v[114:117]
	s_waitcnt lgkmcnt(1)
	v_mfma_f32_16x16x32_bf16 v[60:63], v[204:207], v[64:67], v[60:63]
	v_mfma_f32_16x16x32_bf16 v[64:67], v[204:207], v[72:75], v[40:43]
	s_waitcnt lgkmcnt(0)
	v_mfma_f32_16x16x32_bf16 v[40:43], v[208:211], v[68:71], v[60:63]
	v_mfma_f32_16x16x32_bf16 v[60:63], v[208:211], v[76:79], v[64:67]
	s_waitcnt lgkmcnt(0)
	s_barrier
	ds_write_b32 v201, v88
	ds_write_b32 v201, v89 offset:528
	ds_write_b32 v201, v90 offset:1056
	ds_write_b32 v202, v91
	ds_write_b32 v201, v106 offset:8448
	ds_write_b32 v201, v107 offset:8976
	ds_write_b32 v201, v108 offset:9504
	ds_write_b32 v201, v109 offset:10032
	ds_write_b32 v201, v118 offset:16896
	ds_write_b32 v201, v119 offset:17424
	ds_write_b32 v201, v120 offset:17952
	ds_write_b32 v201, v121 offset:18480
	ds_write_b32 v201, v126 offset:25344
	ds_write_b32 v201, v127 offset:25872
	ds_write_b32 v201, v128 offset:26400
	ds_write_b32 v201, v129 offset:26928
	ds_write_b32 v201, v92 offset:64
	ds_write_b32 v201, v93 offset:592
	ds_write_b32 v201, v94 offset:1120
	ds_write_b32 v202, v95 offset:64
	ds_write_b32 v201, v80 offset:8512
	ds_write_b32 v201, v81 offset:9040
	ds_write_b32 v201, v82 offset:9568
	ds_write_b32 v201, v83 offset:10096
	ds_write_b32 v201, v102 offset:16960
	ds_write_b32 v201, v103 offset:17488
	ds_write_b32 v201, v104 offset:18016
	ds_write_b32 v201, v105 offset:18544
	ds_write_b32 v201, v84 offset:25408
	ds_write_b32 v201, v85 offset:25936
	ds_write_b32 v201, v86 offset:26464
	ds_write_b32 v201, v87 offset:26992
	s_waitcnt lgkmcnt(0)
	s_barrier
	s_mov_b32 s1, s36
	s_cbranch_scc0 .LBB0_988
	s_setprio 0
	s_waitcnt lgkmcnt(0)
	s_barrier
	s_waitcnt lgkmcnt(0)
	s_barrier
	v_mov_b32_e32 v227, 1
	v_mov_b64_e32 v[244:245], 0x100
